# HGRN chunk loop: z/q prefetch loads use SGPR base + shared 32-bit offset (31 64-bit VALU adds -> 15 32-bit), NaN-canonicalising v_max removed
# baseline (speedup 1.0000x reference)
; __device__ __forceinline__ void hgrn_chain(const Params& p, LAS unsigned char* lds, int layer, int chain, int dvh) {
;     ...
;         if (c + 1 < SEQ / 64) { HG_A1(cur ^ 1); if (c + 2 < SEQ / 64) HG_LOAD(c + 2); }
.LBB0_426:
	s_xor_b32 s57, s0, 1
	s_cmpk_lg_i32 s72, 0xf840
	v_cvt_pk_bf16_f32 v34, v35, v36
	v_add_u32_e32 v36, s78, v126
	s_cselect_b64 s[70:71], -1, 0
	s_cmpk_eq_i32 s72, 0xf840
	v_cvt_pk_bf16_f32 v35, v37, v85
	ds_write_b64 v36, v[34:35]
	s_cbranch_scc1 .LBB0_442
	s_waitcnt vmcnt(0)
	v_lshlrev_b32_e32 v34, 16, v92
	v_max_f32_e32 v34, 0xc2700000, v34
	v_mul_f32_e32 v34, 0xbfb8aa3b, v34
	v_exp_f32_e32 v63, v34
	v_lshlrev_b32_e32 v34, 16, v93
	v_max_f32_e32 v34, 0xc2700000, v34
	v_mul_f32_e32 v34, 0xbfb8aa3b, v34
	v_exp_f32_e32 v62, v34
	v_add_f32_e32 v34, 1.0, v63
	v_lshlrev_b32_e32 v43, 16, v96
	v_rcp_f32_e32 v65, v34
	v_add_f32_e32 v34, 1.0, v62
	v_rcp_f32_e32 v64, v34
	v_lshlrev_b32_e32 v34, 16, v95
	v_max_f32_e32 v43, 0xc2700000, v43
	v_mul_f32_e32 v43, 0xbfb8aa3b, v43
	v_max_f32_e32 v34, 0xc2700000, v34
	v_exp_f32_e32 v66, v43
	v_lshlrev_b32_e32 v43, 16, v97
	v_mul_f32_e32 v34, 0xbfb8aa3b, v34
	v_exp_f32_e32 v67, v34
	v_max_f32_e32 v43, 0xc2700000, v43
	v_mul_f32_e32 v43, 0xbfb8aa3b, v43
	v_exp_f32_e32 v71, v43
	v_add_f32_e32 v34, 1.0, v67
	v_rcp_f32_e32 v69, v34
	v_add_f32_e32 v34, 1.0, v66
	v_lshlrev_b32_e32 v43, 16, v99
	v_rcp_f32_e32 v68, v34
	v_add_f32_e32 v34, 1.0, v71
	v_rcp_f32_e32 v73, v34
	v_lshlrev_b32_e32 v34, 16, v98
	v_max_f32_e32 v43, 0xc2700000, v43
	v_mul_f32_e32 v43, 0xbfb8aa3b, v43
	v_max_f32_e32 v34, 0xc2700000, v34
	v_exp_f32_e32 v75, v43
	v_lshlrev_b32_e32 v43, 16, v100
	v_mul_f32_e32 v34, 0xbfb8aa3b, v34
	v_exp_f32_e32 v70, v34
	v_max_f32_e32 v43, 0xc2700000, v43
	v_mul_f32_e32 v43, 0xbfb8aa3b, v43
	v_exp_f32_e32 v74, v43
	v_add_f32_e32 v34, 1.0, v70
	v_rcp_f32_e32 v72, v34
	v_add_f32_e32 v34, 1.0, v75
	v_rcp_f32_e32 v77, v34
	v_add_f32_e32 v34, 1.0, v74
	v_rcp_f32_e32 v76, v34
	v_lshlrev_b32_e32 v34, 16, v101
	v_max_f32_e32 v34, 0xc2700000, v34
	v_lshlrev_b32_e32 v6, 16, v89
	v_mul_f32_e32 v34, 0xbfb8aa3b, v34
	v_exp_f32_e32 v79, v34
	v_max_f32_e32 v6, 0xc2700000, v6
	v_mul_f32_e32 v6, 0xbfb8aa3b, v6
	v_exp_f32_e32 v8, v6
	v_lshlrev_b32_e32 v6, 16, v90
	v_add_f32_e32 v34, 1.0, v79
	v_max_f32_e32 v6, 0xc2700000, v6
	v_rcp_f32_e32 v81, v34
	v_lshlrev_b32_e32 v34, 16, v102
	v_mul_f32_e32 v6, 0xbfb8aa3b, v6
	v_exp_f32_e32 v7, v6
	v_max_f32_e32 v34, 0xc2700000, v34
	v_lshlrev_b32_e32 v43, 16, v104
	v_mul_f32_e32 v34, 0xbfb8aa3b, v34
	v_exp_f32_e32 v78, v34
	v_lshlrev_b32_e32 v34, 16, v103
	v_max_f32_e32 v43, 0xc2700000, v43
	v_add_f32_e32 v6, 1.0, v8
	v_mul_f32_e32 v43, 0xbfb8aa3b, v43
	v_rcp_f32_e32 v35, v6
	v_add_f32_e32 v6, 1.0, v7
	v_max_f32_e32 v34, 0xc2700000, v34
	v_exp_f32_e32 v82, v43
	v_lshlrev_b32_e32 v43, 16, v105
	v_rcp_f32_e32 v9, v6
	v_lshlrev_b32_e32 v6, 16, v91
	v_mul_f32_e32 v34, 0xbfb8aa3b, v34
	v_exp_f32_e32 v83, v34
	v_max_f32_e32 v43, 0xc2700000, v43
	v_max_f32_e32 v6, 0xc2700000, v6
	v_mul_f32_e32 v43, 0xbfb8aa3b, v43
	v_mul_f32_e32 v6, 0xbfb8aa3b, v6
	v_exp_f32_e32 v45, v43
	v_exp_f32_e32 v6, v6
	v_add_f32_e32 v34, 1.0, v78
	v_rcp_f32_e32 v80, v34
	v_add_f32_e32 v34, 1.0, v83
	v_rcp_f32_e32 v85, v34
	v_add_f32_e32 v34, 1.0, v82
	v_rcp_f32_e32 v84, v34
	v_add_f32_e32 v34, 1.0, v45
	v_mul_f32_e32 v37, v40, v8
	v_add_f32_e32 v8, 1.0, v6
	v_rcp_f32_e32 v43, v34
	v_mul_f32_e32 v44, v40, v9
	v_rcp_f32_e32 v8, v8
	v_pk_add_f32 v[46:47], v[38:39], v[44:45]
	v_pk_mul_f32 v[44:45], v[38:39], v[44:45]
	v_fma_f32 v42, v40, v35, v38
	v_mov_b32_e32 v47, v45
	v_pk_mul_f32 v[44:45], v[46:47], v[42:43]
	v_fma_f32 v36, v40, v8, v38
	v_mov_b32_e32 v34, v44
	v_fma_f32 v56, v40, v65, v38
	v_pk_mul_f32 v[46:47], v[34:35], v[36:37]
	v_fma_f32 v57, v40, v64, v38
	v_mul_f32_e32 v106, v46, v56
	v_fma_f32 v58, v40, v69, v38
	v_mul_f32_e32 v107, v106, v57
	v_fma_f32 v59, v40, v68, v38
	v_mul_f32_e32 v108, v107, v58
	v_fma_f32 v60, v40, v73, v38
	v_mul_f32_e32 v109, v108, v59
	v_fma_f32 v61, v40, v72, v38
	v_mul_f32_e32 v110, v109, v60
	v_fma_f32 v112, v40, v77, v38
	v_mul_f32_e32 v111, v110, v61
	v_fma_f32 v113, v40, v76, v38
	v_mul_f32_e32 v112, v111, v112
	v_fma_f32 v114, v40, v81, v38
	v_mul_f32_e32 v113, v112, v113
	v_fma_f32 v115, v40, v80, v38
	v_mul_f32_e32 v114, v113, v114
	v_fma_f32 v116, v40, v85, v38
	v_mul_f32_e32 v115, v114, v115
	v_fma_f32 v117, v40, v84, v38
	v_mul_f32_e32 v116, v115, v116
	v_fma_f32 v118, v40, v43, v38
	v_mul_f32_e32 v117, v116, v117
	v_mul_f32_e32 v118, v117, v118
	v_lshl_add_u32 v34, s57, 11, v94
	ds_write_b32 v34, v118
	s_waitcnt vmcnt(0)
	s_cmp_gt_u32 s56, 29
	v_perm_b32 v152, v194, v195, s87
	v_perm_b32 v151, v196, v197, s87
	v_perm_b32 v150, v198, v199, s87
	v_perm_b32 v149, v200, v201, s87
	v_perm_b32 v148, v202, v203, s87
	v_perm_b32 v147, v204, v205, s87
	v_perm_b32 v146, v206, v207, s87
	v_perm_b32 v145, v208, v209, s87
	v_mov_b64_e32 v[2:3], v[210:211]
	v_mov_b64_e32 v[4:5], v[212:213]
	s_cbranch_scc1 .LBB0_441
	v_cndmask_b32_e64 v34, 0, 1, s[8:9]
	s_mov_b64 s[96:97], -1
	v_cmp_ne_u32_e64 s[0:1], 1, v34
	s_andn2_b64 vcc, exec, s[8:9]
	v_add_u32_e32 v34, s72, v138
	s_cbranch_vccnz .LBB0_432
	v_add_u32_e32 v36, s72, v138
	s_add_i32 s59, s56, 2
	v_lshl_add_u32 v35, s59, 6, v87
	s_cbranch_execz .LBB0_433

.LBB0_436:
	v_ashrrev_i32_e32 v37, 31, v36
	v_lshl_add_u64 v[36:37], s[4:5], 0, v[36:37]
	v_ashrrev_i32_e32 v35, 31, v34
	v_mad_u64_u32 v[56:57], s[96:97], v36, s38, v[48:49]
	v_lshl_add_u64 v[34:35], s[4:5], 0, v[34:35]
	v_mad_i32_i24 v57, v37, s38, v57
	v_mad_u64_u32 v[36:37], s[96:97], v34, s38, v[50:51]
	v_mad_i32_i24 v37, v35, s38, v37
	v_subrev_u32_e32 v34, s90, v56
	v_sub_u32_e32 v35, v36, v56
	s_nop 0
	v_readfirstlane_b32 s96, v35
	s_ashr_i32 s97, s96, 31
	s_add_u32 s96, s90, s96
	s_addc_u32 s97, s91, s97
	global_load_ushort v89, v34, s[90:91]
	global_load_ushort v194, v34, s[96:97]
	v_add_u32_e32 v34, s6, v34
	global_load_ushort v90, v34, s[90:91]
	global_load_ushort v195, v34, s[96:97]
	v_add_u32_e32 v34, s6, v34
	global_load_ushort v91, v34, s[90:91]
	global_load_ushort v196, v34, s[96:97]
	v_add_u32_e32 v34, s6, v34
	global_load_ushort v92, v34, s[90:91]
	global_load_ushort v197, v34, s[96:97]
	v_add_u32_e32 v34, s6, v34
	global_load_ushort v93, v34, s[90:91]
	global_load_ushort v198, v34, s[96:97]
	v_add_u32_e32 v34, s6, v34
	global_load_ushort v95, v34, s[90:91]
	global_load_ushort v199, v34, s[96:97]
	v_add_u32_e32 v34, s6, v34
	global_load_ushort v96, v34, s[90:91]
	global_load_ushort v200, v34, s[96:97]
	v_add_u32_e32 v34, s6, v34
	global_load_ushort v97, v34, s[90:91]
	global_load_ushort v201, v34, s[96:97]
	v_add_u32_e32 v34, s6, v34
	global_load_ushort v98, v34, s[90:91]
	global_load_ushort v202, v34, s[96:97]
	v_add_u32_e32 v34, s6, v34
	global_load_ushort v99, v34, s[90:91]
	global_load_ushort v203, v34, s[96:97]
	v_add_u32_e32 v34, s6, v34
	global_load_ushort v100, v34, s[90:91]
	global_load_ushort v204, v34, s[96:97]
	v_add_u32_e32 v34, s6, v34
	global_load_ushort v101, v34, s[90:91]
	global_load_ushort v205, v34, s[96:97]
	v_add_u32_e32 v34, s6, v34
	global_load_ushort v102, v34, s[90:91]
	global_load_ushort v206, v34, s[96:97]
	v_add_u32_e32 v34, s6, v34
	global_load_ushort v103, v34, s[90:91]
	global_load_ushort v207, v34, s[96:97]
	v_add_u32_e32 v34, s6, v34
	global_load_ushort v104, v34, s[90:91]
	global_load_ushort v208, v34, s[96:97]
	v_add_u32_e32 v34, s6, v34
	global_load_ushort v105, v34, s[90:91]
	global_load_ushort v209, v34, s[96:97]
	s_mov_b64 s[96:97], -1
	s_and_b64 vcc, exec, s[0:1]
	s_cbranch_vccnz .LBB0_438
	v_add_u32_e32 v34, s72, v137
	s_mov_b64 s[96:97], 0
